# RoPE epilogue sections (PREP q/k projection, INPROJ): second cos/sin row loads issued with the first pair, counted vmcnt, stores in between no longer waited
# baseline (speedup 1.0000x reference)
; DI void store4(u16* dst, float a, float b, float c, float d) { *(uint2*)dst = make_uint2(pack2(a, b), pack2(c, d)); }
;     ...
;         if (((nb >> 5) % 3) == 2) {
; #pragma unroll
;           for (int gq = 0; gq < 2; ++gq) {
;             float o1[4], o2[4];
; #pragma unroll
;             for (int r = 0; r < 4; ++r) {
;               int ii = 8 * gq + 4 * hh + r;
;               float c = p.ropec[pos * 16 + ii], sn = p.ropes[pos * 16 + ii];
;               float x1 = acc[i][j][4 * gq + r] * rs, x2 = acc[i][j][4 * (gq + 2) + r] * rs;
;               o1[r] = x1 * c - x2 * sn; o2[r] = x2 * c + x1 * sn;
;             }
;             store4(qrow + nb + 8 * gq + 4 * hh, o1[0], o1[1], o1[2], o1[3]);
;             store4(qrow + nb + 16 + 8 * gq + 4 * hh, o2[0], o2[1], o2[2], o2[3]);
;           }
.LBB0_739:
	s_or_saveexec_b64 s[2:3], s[2:3]
	v_lshlrev_b32_e32 v71, 2, v73
	v_lshl_or_b32 v76, v76, 4, v71
	v_lshl_add_u64 v[78:79], v[66:67], 1, v[78:79]
	v_ashrrev_i32_e32 v77, 31, v76
	v_lshlrev_b32_e32 v0, 1, v71
	s_xor_b64 exec, exec, s[2:3]
	s_cbranch_execz .LBB0_741
	v_lshlrev_b64 v[82:83], 2, v[76:77]
	v_lshl_add_u64 v[94:95], s[50:51], 0, v[82:83]
	v_lshl_add_u64 v[92:93], s[48:49], 0, v[82:83]
	global_load_dwordx4 v[86:89], v[94:95], off
	global_load_dwordx4 v[82:85], v[92:93], off
	global_load_dwordx4 v[108:111], v[94:95], off offset:32
	global_load_dwordx4 v[112:115], v[92:93], off offset:32
	v_pk_mul_f32 v[50:51], v[50:51], v[72:73] op_sel_hi:[1,0]
	v_pk_mul_f32 v[58:59], v[58:59], v[72:73] op_sel_hi:[1,0]
	v_pk_mul_f32 v[52:53], v[52:53], v[72:73] op_sel_hi:[1,0]
	v_lshl_add_u64 v[90:91], v[78:79], 0, v[0:1]
	v_pk_mul_f32 v[54:55], v[54:55], v[72:73] op_sel_hi:[1,0]
	v_pk_mul_f32 v[62:63], v[62:63], v[72:73] op_sel_hi:[1,0]
	s_waitcnt vmcnt(3)
	v_pk_mul_f32 v[96:97], v[50:51], v[86:87]
	s_waitcnt vmcnt(2)
	v_pk_fma_f32 v[96:97], v[58:59], v[82:83], v[96:97]
	v_pk_mul_f32 v[58:59], v[58:59], v[86:87]
	s_nop 0
	v_pk_fma_f32 v[50:51], v[50:51], v[82:83], v[58:59] neg_lo:[0,0,1] neg_hi:[0,0,1]
	v_pk_mul_f32 v[58:59], v[60:61], v[72:73] op_sel_hi:[1,0]
	v_pk_mul_f32 v[60:61], v[52:53], v[88:89]
	v_cvt_pk_bf16_f32 v50, v50, v51
	v_pk_fma_f32 v[60:61], v[58:59], v[84:85], v[60:61]
	v_pk_mul_f32 v[58:59], v[58:59], v[88:89]
	s_nop 0
	v_pk_fma_f32 v[52:53], v[52:53], v[84:85], v[58:59] neg_lo:[0,0,1] neg_hi:[0,0,1]
	s_nop 0
	v_cvt_pk_bf16_f32 v51, v52, v53
	global_store_dwordx2 v[90:91], v[50:51], off
	v_cvt_pk_bf16_f32 v50, v96, v97
	v_cvt_pk_bf16_f32 v51, v60, v61
	global_store_dwordx2 v[90:91], v[50:51], off offset:32
	s_waitcnt vmcnt(3)
	v_pk_mul_f32 v[82:83], v[54:55], v[108:109]
	v_pk_mul_f32 v[58:59], v[62:63], v[108:109]
	s_waitcnt vmcnt(2)
	v_pk_fma_f32 v[82:83], v[62:63], v[112:113], v[82:83]
	v_pk_fma_f32 v[50:51], v[54:55], v[112:113], v[58:59] neg_lo:[0,0,1] neg_hi:[0,0,1]
	v_pk_mul_f32 v[54:55], v[56:57], v[72:73] op_sel_hi:[1,0]
	v_pk_mul_f32 v[56:57], v[64:65], v[72:73] op_sel_hi:[1,0]
	v_pk_mul_f32 v[58:59], v[54:55], v[110:111]
	v_cvt_pk_bf16_f32 v50, v50, v51
	v_pk_fma_f32 v[58:59], v[56:57], v[114:115], v[58:59]
	v_pk_mul_f32 v[56:57], v[56:57], v[110:111]
	s_nop 0
	v_pk_fma_f32 v[52:53], v[54:55], v[114:115], v[56:57] neg_lo:[0,0,1] neg_hi:[0,0,1]
	s_nop 0
	v_cvt_pk_bf16_f32 v51, v52, v53
	global_store_dwordx2 v[90:91], v[50:51], off offset:16
	v_cvt_pk_bf16_f32 v50, v82, v83
	v_cvt_pk_bf16_f32 v51, v58, v59
	global_store_dwordx2 v[90:91], v[50:51], off offset:48

; DI void store4(u16* dst, float a, float b, float c, float d) { *(uint2*)dst = make_uint2(pack2(a, b), pack2(c, d)); }
;     ...
;         if (((nb >> 5) % 3) == 2) {
; #pragma unroll
;           for (int gq = 0; gq < 2; ++gq) {
;             float o1[4], o2[4];
; #pragma unroll
;             for (int r = 0; r < 4; ++r) {
;               int ii = 8 * gq + 4 * hh + r;
;               float c = p.ropec[pos * 16 + ii], sn = p.ropes[pos * 16 + ii];
;               float x1 = acc[i][j][4 * gq + r] * rs, x2 = acc[i][j][4 * (gq + 2) + r] * rs;
;               o1[r] = x1 * c - x2 * sn; o2[r] = x2 * c + x1 * sn;
;             }
;             store4(qrow + nb + 8 * gq + 4 * hh, o1[0], o1[1], o1[2], o1[3]);
;             store4(qrow + nb + 16 + 8 * gq + 4 * hh, o2[0], o2[1], o2[2], o2[3]);
;           }
.LBB0_743:
	s_andn2_saveexec_b64 s[2:3], s[2:3]
	s_cbranch_execz .LBB0_745
	v_lshlrev_b64 v[50:51], 2, v[76:77]
	v_lshl_add_u64 v[62:63], s[50:51], 0, v[50:51]
	v_lshl_add_u64 v[60:61], s[48:49], 0, v[50:51]
	global_load_dwordx4 v[54:57], v[62:63], off
	global_load_dwordx4 v[50:53], v[60:61], off
	global_load_dwordx4 v[108:111], v[62:63], off offset:32
	global_load_dwordx4 v[112:115], v[60:61], off offset:32
	v_pk_mul_f32 v[34:35], v[34:35], v[72:73] op_sel_hi:[1,0]
	v_pk_mul_f32 v[42:43], v[42:43], v[72:73] op_sel_hi:[1,0]
	v_pk_mul_f32 v[36:37], v[36:37], v[72:73] op_sel_hi:[1,0]
	v_lshl_add_u64 v[58:59], v[78:79], 0, v[0:1]
	v_pk_mul_f32 v[38:39], v[38:39], v[72:73] op_sel_hi:[1,0]
	v_pk_mul_f32 v[46:47], v[46:47], v[72:73] op_sel_hi:[1,0]
	s_waitcnt vmcnt(3)
	v_pk_mul_f32 v[64:65], v[34:35], v[54:55]
	s_waitcnt vmcnt(2)
	v_pk_fma_f32 v[64:65], v[42:43], v[50:51], v[64:65]
	v_pk_mul_f32 v[42:43], v[42:43], v[54:55]
	s_nop 0
	v_pk_fma_f32 v[34:35], v[34:35], v[50:51], v[42:43] neg_lo:[0,0,1] neg_hi:[0,0,1]
	v_pk_mul_f32 v[42:43], v[44:45], v[72:73] op_sel_hi:[1,0]
	v_pk_mul_f32 v[44:45], v[36:37], v[56:57]
	v_cvt_pk_bf16_f32 v34, v34, v35
	v_pk_fma_f32 v[44:45], v[42:43], v[52:53], v[44:45]
	v_pk_mul_f32 v[42:43], v[42:43], v[56:57]
	s_nop 0
	v_pk_fma_f32 v[36:37], v[36:37], v[52:53], v[42:43] neg_lo:[0,0,1] neg_hi:[0,0,1]
	s_nop 0
	v_cvt_pk_bf16_f32 v35, v36, v37
	global_store_dwordx2 v[58:59], v[34:35], off offset:64
	v_cvt_pk_bf16_f32 v34, v64, v65
	v_cvt_pk_bf16_f32 v35, v44, v45
	global_store_dwordx2 v[58:59], v[34:35], off offset:96
	s_waitcnt vmcnt(3)
	v_pk_mul_f32 v[50:51], v[38:39], v[108:109]
	v_pk_mul_f32 v[42:43], v[46:47], v[108:109]
	s_waitcnt vmcnt(2)
	v_pk_fma_f32 v[50:51], v[46:47], v[112:113], v[50:51]
	v_pk_fma_f32 v[34:35], v[38:39], v[112:113], v[42:43] neg_lo:[0,0,1] neg_hi:[0,0,1]
	v_pk_mul_f32 v[38:39], v[40:41], v[72:73] op_sel_hi:[1,0]
	v_pk_mul_f32 v[40:41], v[48:49], v[72:73] op_sel_hi:[1,0]
	v_pk_mul_f32 v[42:43], v[38:39], v[110:111]
	v_cvt_pk_bf16_f32 v34, v34, v35
	v_pk_fma_f32 v[42:43], v[40:41], v[114:115], v[42:43]
	v_pk_mul_f32 v[40:41], v[40:41], v[110:111]
	s_nop 0
	v_pk_fma_f32 v[36:37], v[38:39], v[114:115], v[40:41] neg_lo:[0,0,1] neg_hi:[0,0,1]
	s_nop 0
	v_cvt_pk_bf16_f32 v35, v36, v37
	global_store_dwordx2 v[58:59], v[34:35], off offset:80
	v_cvt_pk_bf16_f32 v34, v50, v51
	v_cvt_pk_bf16_f32 v35, v42, v43
	global_store_dwordx2 v[58:59], v[34:35], off offset:112

; DI void store4(u16* dst, float a, float b, float c, float d) { *(uint2*)dst = make_uint2(pack2(a, b), pack2(c, d)); }
;     ...
;         if (((nb >> 5) % 3) == 2) {
; #pragma unroll
;           for (int gq = 0; gq < 2; ++gq) {
;             float o1[4], o2[4];
; #pragma unroll
;             for (int r = 0; r < 4; ++r) {
;               int ii = 8 * gq + 4 * hh + r;
;               float c = p.ropec[pos * 16 + ii], sn = p.ropes[pos * 16 + ii];
;               float x1 = acc[i][j][4 * gq + r] * rs, x2 = acc[i][j][4 * (gq + 2) + r] * rs;
;               o1[r] = x1 * c - x2 * sn; o2[r] = x2 * c + x1 * sn;
;             }
;             store4(qrow + nb + 8 * gq + 4 * hh, o1[0], o1[1], o1[2], o1[3]);
;             store4(qrow + nb + 16 + 8 * gq + 4 * hh, o2[0], o2[1], o2[2], o2[3]);
;           }
.LBB0_751:
	s_or_saveexec_b64 s[2:3], s[2:3]
	v_lshl_or_b32 v38, v38, 4, v71
	v_lshl_add_u64 v[40:41], v[66:67], 1, v[40:41]
	v_ashrrev_i32_e32 v39, 31, v38
	s_xor_b64 exec, exec, s[2:3]
	s_cbranch_execz .LBB0_754
	v_lshlrev_b64 v[42:43], 2, v[38:39]
	v_lshl_add_u64 v[54:55], s[50:51], 0, v[42:43]
	v_lshl_add_u64 v[52:53], s[48:49], 0, v[42:43]
	global_load_dwordx4 v[46:49], v[54:55], off
	global_load_dwordx4 v[42:45], v[52:53], off
	global_load_dwordx4 v[108:111], v[54:55], off offset:32
	global_load_dwordx4 v[112:115], v[52:53], off offset:32
	v_pk_mul_f32 v[18:19], v[18:19], v[34:35] op_sel_hi:[1,0]
	v_pk_mul_f32 v[26:27], v[26:27], v[34:35] op_sel_hi:[1,0]
	v_pk_mul_f32 v[20:21], v[20:21], v[34:35] op_sel_hi:[1,0]
	v_lshl_add_u64 v[50:51], v[40:41], 0, v[0:1]
	v_pk_mul_f32 v[22:23], v[22:23], v[34:35] op_sel_hi:[1,0]
	v_pk_mul_f32 v[30:31], v[30:31], v[34:35] op_sel_hi:[1,0]
	s_waitcnt vmcnt(3)
	v_pk_mul_f32 v[56:57], v[18:19], v[46:47]
	s_waitcnt vmcnt(2)
	v_pk_fma_f32 v[56:57], v[26:27], v[42:43], v[56:57]
	v_pk_mul_f32 v[26:27], v[26:27], v[46:47]
	s_nop 0
	v_pk_fma_f32 v[18:19], v[18:19], v[42:43], v[26:27] neg_lo:[0,0,1] neg_hi:[0,0,1]
	v_pk_mul_f32 v[26:27], v[28:29], v[34:35] op_sel_hi:[1,0]
	v_pk_mul_f32 v[28:29], v[20:21], v[48:49]
	v_cvt_pk_bf16_f32 v18, v18, v19
	v_pk_fma_f32 v[28:29], v[26:27], v[44:45], v[28:29]
	v_pk_mul_f32 v[26:27], v[26:27], v[48:49]
	s_nop 0
	v_pk_fma_f32 v[20:21], v[20:21], v[44:45], v[26:27] neg_lo:[0,0,1] neg_hi:[0,0,1]
	s_nop 0
	v_cvt_pk_bf16_f32 v19, v20, v21
	global_store_dwordx2 v[50:51], v[18:19], off
	v_cvt_pk_bf16_f32 v18, v56, v57
	v_cvt_pk_bf16_f32 v19, v28, v29
	global_store_dwordx2 v[50:51], v[18:19], off offset:32
	s_waitcnt vmcnt(3)
	v_pk_mul_f32 v[42:43], v[22:23], v[108:109]
	v_pk_mul_f32 v[26:27], v[30:31], v[108:109]
	s_waitcnt vmcnt(2)
	v_pk_fma_f32 v[42:43], v[30:31], v[112:113], v[42:43]
	v_pk_fma_f32 v[18:19], v[22:23], v[112:113], v[26:27] neg_lo:[0,0,1] neg_hi:[0,0,1]
	v_pk_mul_f32 v[22:23], v[24:25], v[34:35] op_sel_hi:[1,0]
	v_pk_mul_f32 v[24:25], v[32:33], v[34:35] op_sel_hi:[1,0]
	v_pk_mul_f32 v[26:27], v[22:23], v[110:111]
	v_cvt_pk_bf16_f32 v18, v18, v19
	v_pk_fma_f32 v[26:27], v[24:25], v[114:115], v[26:27]
	v_pk_mul_f32 v[24:25], v[24:25], v[110:111]
	s_nop 0
	v_pk_fma_f32 v[20:21], v[22:23], v[114:115], v[24:25] neg_lo:[0,0,1] neg_hi:[0,0,1]
	s_nop 0
	v_cvt_pk_bf16_f32 v19, v20, v21
	global_store_dwordx2 v[50:51], v[18:19], off offset:16
	v_cvt_pk_bf16_f32 v18, v42, v43
	v_cvt_pk_bf16_f32 v19, v26, v27
	global_store_dwordx2 v[50:51], v[18:19], off offset:48
	s_or_b64 exec, exec, s[2:3]
	s_and_saveexec_b64 s[2:3], s[42:43]
	s_xor_b64 s[2:3], exec, s[2:3]
	s_cbranch_execnz .LBB0_755

; DI void store4(u16* dst, float a, float b, float c, float d) { *(uint2*)dst = make_uint2(pack2(a, b), pack2(c, d)); }
;     ...
;         if (nb == 384) {
;           u16* kr = (u16*)p.out + (size_t)TP * 1024 + (size_t)TP * 768 + (size_t)m * 32;
; #pragma unroll
;           for (int gq = 0; gq < 2; ++gq) {
;             float o1[4], o2[4];
; #pragma unroll
;             for (int r = 0; r < 4; ++r) {
;               int ii = 8 * gq + 4 * hh + r;
;               float c = p.ropec[pos * 16 + ii], sn = p.ropes[pos * 16 + ii];
;               float x1 = acc[i][j][4 * gq + r] * rs, x2 = acc[i][j][4 * (gq + 2) + r] * rs;
;               o1[r] = x1 * c - x2 * sn; o2[r] = x2 * c + x1 * sn;
;             }
;             store4(kr + 8 * gq + 4 * hh, o1[0], o1[1], o1[2], o1[3]);
;             store4(kr + 16 + 8 * gq + 4 * hh, o2[0], o2[1], o2[2], o2[3]);
;           }
.LBB0_849:
	s_or_saveexec_b64 s[2:3], s[2:3]
	v_lshlrev_b32_e32 v136, 1, v0
	s_xor_b64 exec, exec, s[2:3]
	s_cbranch_execz .LBB0_851
	v_lshlrev_b64 v[150:151], 6, v[130:131]
	v_lshl_add_u64 v[150:151], s[80:81], 0, v[150:151]
	v_mov_b32_e32 v137, v1
	v_lshl_add_u64 v[160:161], v[150:151], 0, v[136:137]
	v_lshl_or_b32 v150, v133, 4, v0
	v_ashrrev_i32_e32 v151, 31, v150
	v_lshlrev_b64 v[150:151], 2, v[150:151]
	v_lshl_add_u64 v[164:165], s[66:67], 0, v[150:151]
	v_lshl_add_u64 v[162:163], s[64:65], 0, v[150:151]
	global_load_dwordx4 v[156:159], v[164:165], off
	global_load_dwordx4 v[150:153], v[162:163], off
	global_load_dwordx4 v[204:207], v[164:165], off offset:32
	global_load_dwordx4 v[208:211], v[162:163], off offset:32
	s_waitcnt lgkmcnt(0)
	v_pk_mul_f32 v[114:115], v[114:115], v[138:139] op_sel_hi:[1,0]
	v_pk_mul_f32 v[122:123], v[122:123], v[138:139] op_sel_hi:[1,0]
	v_pk_mul_f32 v[116:117], v[116:117], v[138:139] op_sel_hi:[1,0]
	v_pk_mul_f32 v[118:119], v[118:119], v[138:139] op_sel_hi:[1,0]
	v_pk_mul_f32 v[126:127], v[126:127], v[138:139] op_sel_hi:[1,0]
	v_mov_b32_e32 v137, 0
	s_waitcnt vmcnt(3)
	v_pk_mul_f32 v[166:167], v[114:115], v[156:157]
	s_waitcnt vmcnt(2)
	v_pk_fma_f32 v[166:167], v[122:123], v[150:151], v[166:167]
	v_pk_mul_f32 v[122:123], v[122:123], v[156:157]
	s_nop 0
	v_pk_fma_f32 v[114:115], v[114:115], v[150:151], v[122:123] neg_lo:[0,0,1] neg_hi:[0,0,1]
	v_pk_mul_f32 v[122:123], v[124:125], v[138:139] op_sel_hi:[1,0]
	v_pk_mul_f32 v[124:125], v[116:117], v[158:159]
	v_cvt_pk_bf16_f32 v114, v114, v115
	v_pk_fma_f32 v[124:125], v[122:123], v[152:153], v[124:125]
	v_pk_mul_f32 v[122:123], v[122:123], v[158:159]
	s_nop 0
	v_pk_fma_f32 v[116:117], v[116:117], v[152:153], v[122:123] neg_lo:[0,0,1] neg_hi:[0,0,1]
	s_nop 0
	v_cvt_pk_bf16_f32 v115, v116, v117
	global_store_dwordx2 v[160:161], v[114:115], off
	v_cvt_pk_bf16_f32 v114, v166, v167
	v_cvt_pk_bf16_f32 v115, v124, v125
	global_store_dwordx2 v[160:161], v[114:115], off offset:32
	s_waitcnt vmcnt(3)
	v_pk_mul_f32 v[150:151], v[118:119], v[204:205]
	v_pk_mul_f32 v[122:123], v[126:127], v[204:205]
	s_waitcnt vmcnt(2)
	v_pk_fma_f32 v[150:151], v[126:127], v[208:209], v[150:151]
	v_pk_fma_f32 v[114:115], v[118:119], v[208:209], v[122:123] neg_lo:[0,0,1] neg_hi:[0,0,1]
	v_pk_mul_f32 v[118:119], v[120:121], v[138:139] op_sel_hi:[1,0]
	v_pk_mul_f32 v[120:121], v[128:129], v[138:139] op_sel_hi:[1,0]
	v_pk_mul_f32 v[122:123], v[118:119], v[206:207]
	v_cvt_pk_bf16_f32 v114, v114, v115
	v_pk_fma_f32 v[122:123], v[120:121], v[210:211], v[122:123]
	v_pk_mul_f32 v[120:121], v[120:121], v[206:207]
	s_nop 0
	v_pk_fma_f32 v[116:117], v[118:119], v[210:211], v[120:121] neg_lo:[0,0,1] neg_hi:[0,0,1]
	s_nop 0
	v_cvt_pk_bf16_f32 v115, v116, v117
	global_store_dwordx2 v[160:161], v[114:115], off offset:16
	v_cvt_pk_bf16_f32 v114, v150, v151
	v_cvt_pk_bf16_f32 v115, v122, v123
	global_store_dwordx2 v[160:161], v[114:115], off offset:48

; DI void store4(u16* dst, float a, float b, float c, float d) { *(uint2*)dst = make_uint2(pack2(a, b), pack2(c, d)); }
;     ...
;         if (nb == 384) {
;           u16* kr = (u16*)p.out + (size_t)TP * 1024 + (size_t)TP * 768 + (size_t)m * 32;
; #pragma unroll
;           for (int gq = 0; gq < 2; ++gq) {
;             float o1[4], o2[4];
; #pragma unroll
;             for (int r = 0; r < 4; ++r) {
;               int ii = 8 * gq + 4 * hh + r;
;               float c = p.ropec[pos * 16 + ii], sn = p.ropes[pos * 16 + ii];
;               float x1 = acc[i][j][4 * gq + r] * rs, x2 = acc[i][j][4 * (gq + 2) + r] * rs;
;               o1[r] = x1 * c - x2 * sn; o2[r] = x2 * c + x1 * sn;
;             }
;             store4(kr + 8 * gq + 4 * hh, o1[0], o1[1], o1[2], o1[3]);
;             store4(kr + 16 + 8 * gq + 4 * hh, o2[0], o2[1], o2[2], o2[3]);
;           }
.LBB0_940:
	s_andn2_saveexec_b64 s[2:3], s[2:3]
	s_cbranch_execz .LBB0_942
	v_lshl_or_b32 v116, v116, 4, v0
	v_ashrrev_i32_e32 v117, 31, v116
	v_lshlrev_b64 v[116:117], 2, v[116:117]
	v_lshl_add_u64 v[126:127], s[66:67], 0, v[116:117]
	v_lshl_add_u64 v[124:125], s[64:65], 0, v[116:117]
	global_load_dwordx4 v[120:123], v[126:127], off
	global_load_dwordx4 v[116:119], v[124:125], off
	global_load_dwordx4 v[204:207], v[126:127], off offset:32
	global_load_dwordx4 v[208:211], v[124:125], off offset:32
	s_waitcnt lgkmcnt(0)
	v_pk_mul_f32 v[82:83], v[82:83], v[100:101] op_sel_hi:[1,0]
	v_pk_mul_f32 v[90:91], v[90:91], v[100:101] op_sel_hi:[1,0]
	v_pk_mul_f32 v[84:85], v[84:85], v[100:101] op_sel_hi:[1,0]
	v_lshlrev_b64 v[106:107], 6, v[106:107]
	v_lshl_add_u64 v[106:107], s[80:81], 0, v[106:107]
	v_mov_b32_e32 v137, v1
	v_lshl_add_u64 v[106:107], v[106:107], 0, v[136:137]
	v_pk_mul_f32 v[86:87], v[86:87], v[100:101] op_sel_hi:[1,0]
	v_pk_mul_f32 v[94:95], v[94:95], v[100:101] op_sel_hi:[1,0]
	v_mov_b32_e32 v113, 0
	s_waitcnt vmcnt(3)
	v_pk_mul_f32 v[128:129], v[82:83], v[120:121]
	s_waitcnt vmcnt(2)
	v_pk_fma_f32 v[128:129], v[90:91], v[116:117], v[128:129]
	v_pk_mul_f32 v[90:91], v[90:91], v[120:121]
	s_nop 0
	v_pk_fma_f32 v[82:83], v[82:83], v[116:117], v[90:91] neg_lo:[0,0,1] neg_hi:[0,0,1]
	v_pk_mul_f32 v[90:91], v[92:93], v[100:101] op_sel_hi:[1,0]
	v_pk_mul_f32 v[92:93], v[84:85], v[122:123]
	v_cvt_pk_bf16_f32 v82, v82, v83
	v_pk_fma_f32 v[92:93], v[90:91], v[118:119], v[92:93]
	v_pk_mul_f32 v[90:91], v[90:91], v[122:123]
	s_nop 0
	v_pk_fma_f32 v[84:85], v[84:85], v[118:119], v[90:91] neg_lo:[0,0,1] neg_hi:[0,0,1]
	s_nop 0
	v_cvt_pk_bf16_f32 v83, v84, v85
	global_store_dwordx2 v[106:107], v[82:83], off
	v_cvt_pk_bf16_f32 v82, v128, v129
	v_cvt_pk_bf16_f32 v83, v92, v93
	global_store_dwordx2 v[106:107], v[82:83], off offset:32
	s_waitcnt vmcnt(3)
	v_pk_mul_f32 v[116:117], v[86:87], v[204:205]
	v_pk_mul_f32 v[90:91], v[94:95], v[204:205]
	s_waitcnt vmcnt(2)
	v_pk_fma_f32 v[116:117], v[94:95], v[208:209], v[116:117]
	v_pk_fma_f32 v[82:83], v[86:87], v[208:209], v[90:91] neg_lo:[0,0,1] neg_hi:[0,0,1]
	v_pk_mul_f32 v[86:87], v[88:89], v[100:101] op_sel_hi:[1,0]
	v_pk_mul_f32 v[88:89], v[96:97], v[100:101] op_sel_hi:[1,0]
	v_pk_mul_f32 v[90:91], v[86:87], v[206:207]
	v_cvt_pk_bf16_f32 v82, v82, v83
	v_pk_fma_f32 v[90:91], v[88:89], v[210:211], v[90:91]
	v_pk_mul_f32 v[88:89], v[88:89], v[206:207]
	s_nop 0
	v_pk_fma_f32 v[84:85], v[86:87], v[210:211], v[88:89] neg_lo:[0,0,1] neg_hi:[0,0,1]
	s_nop 0
	v_cvt_pk_bf16_f32 v83, v84, v85
	global_store_dwordx2 v[106:107], v[82:83], off offset:16
	v_cvt_pk_bf16_f32 v82, v116, v117
	v_cvt_pk_bf16_f32 v83, v90, v91
	global_store_dwordx2 v[106:107], v[82:83], off offset:48

; DI void store4(u16* dst, float a, float b, float c, float d) { *(uint2*)dst = make_uint2(pack2(a, b), pack2(c, d)); }
;     ...
;         if (nb == 384) {
;           u16* kr = (u16*)p.out + (size_t)TP * 1024 + (size_t)TP * 768 + (size_t)m * 32;
; #pragma unroll
;           for (int gq = 0; gq < 2; ++gq) {
;             float o1[4], o2[4];
; #pragma unroll
;             for (int r = 0; r < 4; ++r) {
;               int ii = 8 * gq + 4 * hh + r;
;               float c = p.ropec[pos * 16 + ii], sn = p.ropes[pos * 16 + ii];
;               float x1 = acc[i][j][4 * gq + r] * rs, x2 = acc[i][j][4 * (gq + 2) + r] * rs;
;               o1[r] = x1 * c - x2 * sn; o2[r] = x2 * c + x1 * sn;
;             }
;             store4(kr + 8 * gq + 4 * hh, o1[0], o1[1], o1[2], o1[3]);
;             store4(kr + 16 + 8 * gq + 4 * hh, o2[0], o2[1], o2[2], o2[3]);
;           }
.LBB0_1031:
	s_andn2_saveexec_b64 s[2:3], s[2:3]
	s_cbranch_execz .LBB0_1033
	v_lshl_or_b32 v80, v80, 4, v0
	v_ashrrev_i32_e32 v81, 31, v80
	v_lshlrev_b64 v[80:81], 2, v[80:81]
	v_lshl_add_u64 v[90:91], s[66:67], 0, v[80:81]
	v_lshl_add_u64 v[88:89], s[64:65], 0, v[80:81]
	global_load_dwordx4 v[84:87], v[90:91], off
	global_load_dwordx4 v[80:83], v[88:89], off
	global_load_dwordx4 v[204:207], v[90:91], off offset:32
	global_load_dwordx4 v[208:211], v[88:89], off offset:32
	s_waitcnt lgkmcnt(0)
	v_pk_mul_f32 v[50:51], v[50:51], v[66:67] op_sel_hi:[1,0]
	v_pk_mul_f32 v[58:59], v[58:59], v[66:67] op_sel_hi:[1,0]
	v_pk_mul_f32 v[52:53], v[52:53], v[66:67] op_sel_hi:[1,0]
	v_lshlrev_b64 v[72:73], 6, v[72:73]
	v_lshl_add_u64 v[72:73], s[80:81], 0, v[72:73]
	v_mov_b32_e32 v137, v1
	v_lshl_add_u64 v[72:73], v[72:73], 0, v[136:137]
	v_pk_mul_f32 v[54:55], v[54:55], v[66:67] op_sel_hi:[1,0]
	v_pk_mul_f32 v[62:63], v[62:63], v[66:67] op_sel_hi:[1,0]
	v_mov_b32_e32 v79, 0
	s_waitcnt vmcnt(3)
	v_pk_mul_f32 v[92:93], v[50:51], v[84:85]
	s_waitcnt vmcnt(2)
	v_pk_fma_f32 v[92:93], v[58:59], v[80:81], v[92:93]
	v_pk_mul_f32 v[58:59], v[58:59], v[84:85]
	s_nop 0
	v_pk_fma_f32 v[50:51], v[50:51], v[80:81], v[58:59] neg_lo:[0,0,1] neg_hi:[0,0,1]
	v_pk_mul_f32 v[58:59], v[60:61], v[66:67] op_sel_hi:[1,0]
	v_pk_mul_f32 v[60:61], v[52:53], v[86:87]
	v_cvt_pk_bf16_f32 v50, v50, v51
	v_pk_fma_f32 v[60:61], v[58:59], v[82:83], v[60:61]
	v_pk_mul_f32 v[58:59], v[58:59], v[86:87]
	s_nop 0
	v_pk_fma_f32 v[52:53], v[52:53], v[82:83], v[58:59] neg_lo:[0,0,1] neg_hi:[0,0,1]
	s_nop 0
	v_cvt_pk_bf16_f32 v51, v52, v53
	global_store_dwordx2 v[72:73], v[50:51], off
	v_cvt_pk_bf16_f32 v50, v92, v93
	v_cvt_pk_bf16_f32 v51, v60, v61
	global_store_dwordx2 v[72:73], v[50:51], off offset:32
	s_waitcnt vmcnt(3)
	v_pk_mul_f32 v[80:81], v[54:55], v[204:205]
	v_pk_mul_f32 v[58:59], v[62:63], v[204:205]
	s_waitcnt vmcnt(2)
	v_pk_fma_f32 v[80:81], v[62:63], v[208:209], v[80:81]
	v_pk_fma_f32 v[50:51], v[54:55], v[208:209], v[58:59] neg_lo:[0,0,1] neg_hi:[0,0,1]
	v_pk_mul_f32 v[54:55], v[56:57], v[66:67] op_sel_hi:[1,0]
	v_pk_mul_f32 v[56:57], v[64:65], v[66:67] op_sel_hi:[1,0]
	v_pk_mul_f32 v[58:59], v[54:55], v[206:207]
	v_cvt_pk_bf16_f32 v50, v50, v51
	v_pk_fma_f32 v[58:59], v[56:57], v[210:211], v[58:59]
	v_pk_mul_f32 v[56:57], v[56:57], v[206:207]
	s_nop 0
	v_pk_fma_f32 v[52:53], v[54:55], v[210:211], v[56:57] neg_lo:[0,0,1] neg_hi:[0,0,1]
	s_nop 0
	v_cvt_pk_bf16_f32 v51, v52, v53
	global_store_dwordx2 v[72:73], v[50:51], off offset:16
	v_cvt_pk_bf16_f32 v50, v80, v81
	v_cvt_pk_bf16_f32 v51, v58, v59
	global_store_dwordx2 v[72:73], v[50:51], off offset:48

; DI void store4(u16* dst, float a, float b, float c, float d) { *(uint2*)dst = make_uint2(pack2(a, b), pack2(c, d)); }
;     ...
;         if (nb == 384) {
;           u16* kr = (u16*)p.out + (size_t)TP * 1024 + (size_t)TP * 768 + (size_t)m * 32;
; #pragma unroll
;           for (int gq = 0; gq < 2; ++gq) {
;             float o1[4], o2[4];
; #pragma unroll
;             for (int r = 0; r < 4; ++r) {
;               int ii = 8 * gq + 4 * hh + r;
;               float c = p.ropec[pos * 16 + ii], sn = p.ropes[pos * 16 + ii];
;               float x1 = acc[i][j][4 * gq + r] * rs, x2 = acc[i][j][4 * (gq + 2) + r] * rs;
;               o1[r] = x1 * c - x2 * sn; o2[r] = x2 * c + x1 * sn;
;             }
;             store4(kr + 8 * gq + 4 * hh, o1[0], o1[1], o1[2], o1[3]);
;             store4(kr + 16 + 8 * gq + 4 * hh, o2[0], o2[1], o2[2], o2[3]);
;           }
.LBB0_1122:
	s_andn2_saveexec_b64 s[2:3], s[2:3]
	s_cbranch_execz .LBB0_1124
	v_lshl_or_b32 v48, v48, 4, v0
	v_ashrrev_i32_e32 v49, 31, v48
	v_lshlrev_b64 v[48:49], 2, v[48:49]
	v_lshl_add_u64 v[58:59], s[66:67], 0, v[48:49]
	v_lshl_add_u64 v[56:57], s[64:65], 0, v[48:49]
	global_load_dwordx4 v[52:55], v[58:59], off
	global_load_dwordx4 v[48:51], v[56:57], off
	global_load_dwordx4 v[204:207], v[58:59], off offset:32
	global_load_dwordx4 v[208:211], v[56:57], off offset:32
	s_waitcnt lgkmcnt(0)
	v_pk_mul_f32 v[18:19], v[18:19], v[34:35] op_sel_hi:[1,0]
	v_pk_mul_f32 v[26:27], v[26:27], v[34:35] op_sel_hi:[1,0]
	v_pk_mul_f32 v[20:21], v[20:21], v[34:35] op_sel_hi:[1,0]
	v_lshlrev_b64 v[40:41], 6, v[40:41]
	v_lshl_add_u64 v[40:41], s[80:81], 0, v[40:41]
	v_mov_b32_e32 v137, v1
	v_lshl_add_u64 v[40:41], v[40:41], 0, v[136:137]
	v_pk_mul_f32 v[22:23], v[22:23], v[34:35] op_sel_hi:[1,0]
	v_pk_mul_f32 v[30:31], v[30:31], v[34:35] op_sel_hi:[1,0]
	v_mov_b32_e32 v47, 0
	s_waitcnt vmcnt(3)
	v_pk_mul_f32 v[60:61], v[18:19], v[52:53]
	s_waitcnt vmcnt(2)
	v_pk_fma_f32 v[60:61], v[26:27], v[48:49], v[60:61]
	v_pk_mul_f32 v[26:27], v[26:27], v[52:53]
	s_nop 0
	v_pk_fma_f32 v[18:19], v[18:19], v[48:49], v[26:27] neg_lo:[0,0,1] neg_hi:[0,0,1]
	v_pk_mul_f32 v[26:27], v[28:29], v[34:35] op_sel_hi:[1,0]
	v_pk_mul_f32 v[28:29], v[20:21], v[54:55]
	v_cvt_pk_bf16_f32 v18, v18, v19
	v_pk_fma_f32 v[28:29], v[26:27], v[50:51], v[28:29]
	v_pk_mul_f32 v[26:27], v[26:27], v[54:55]
	s_nop 0
	v_pk_fma_f32 v[20:21], v[20:21], v[50:51], v[26:27] neg_lo:[0,0,1] neg_hi:[0,0,1]
	s_nop 0
	v_cvt_pk_bf16_f32 v19, v20, v21
	global_store_dwordx2 v[40:41], v[18:19], off
	v_cvt_pk_bf16_f32 v18, v60, v61
	v_cvt_pk_bf16_f32 v19, v28, v29
	global_store_dwordx2 v[40:41], v[18:19], off offset:32
	s_waitcnt vmcnt(3)
	v_pk_mul_f32 v[48:49], v[22:23], v[204:205]
	v_pk_mul_f32 v[26:27], v[30:31], v[204:205]
	s_waitcnt vmcnt(2)
	v_pk_fma_f32 v[48:49], v[30:31], v[208:209], v[48:49]
	v_pk_fma_f32 v[18:19], v[22:23], v[208:209], v[26:27] neg_lo:[0,0,1] neg_hi:[0,0,1]
	v_pk_mul_f32 v[22:23], v[24:25], v[34:35] op_sel_hi:[1,0]
	v_pk_mul_f32 v[24:25], v[32:33], v[34:35] op_sel_hi:[1,0]
	v_pk_mul_f32 v[26:27], v[22:23], v[206:207]
	v_cvt_pk_bf16_f32 v18, v18, v19
	v_pk_fma_f32 v[26:27], v[24:25], v[210:211], v[26:27]
	v_pk_mul_f32 v[24:25], v[24:25], v[206:207]
	s_nop 0
	v_pk_fma_f32 v[20:21], v[22:23], v[210:211], v[24:25] neg_lo:[0,0,1] neg_hi:[0,0,1]
	s_nop 0
	v_cvt_pk_bf16_f32 v19, v20, v21
	global_store_dwordx2 v[40:41], v[18:19], off offset:16
	v_cvt_pk_bf16_f32 v18, v48, v49
	v_cvt_pk_bf16_f32 v19, v26, v27
	global_store_dwordx2 v[40:41], v[18:19], off offset:48

; DI void store4(u16* dst, float a, float b, float c, float d) { *(uint2*)dst = make_uint2(pack2(a, b), pack2(c, d)); }
;     ...
;         if (nb == 384) {
;           u16* kr = (u16*)p.out + (size_t)TP * 1024 + (size_t)TP * 768 + (size_t)m * 32;
; #pragma unroll
;           for (int gq = 0; gq < 2; ++gq) {
;             float o1[4], o2[4];
; #pragma unroll
;             for (int r = 0; r < 4; ++r) {
;               int ii = 8 * gq + 4 * hh + r;
;               float c = p.ropec[pos * 16 + ii], sn = p.ropes[pos * 16 + ii];
;               float x1 = acc[i][j][4 * gq + r] * rs, x2 = acc[i][j][4 * (gq + 2) + r] * rs;
;               o1[r] = x1 * c - x2 * sn; o2[r] = x2 * c + x1 * sn;
;             }
;             store4(kr + 8 * gq + 4 * hh, o1[0], o1[1], o1[2], o1[3]);
;             store4(kr + 16 + 8 * gq + 4 * hh, o2[0], o2[1], o2[2], o2[3]);
;           }
.LBB0_1217:
	v_lshl_or_b32 v44, v57, 4, v36
	v_ashrrev_i32_e32 v45, 31, v44
	v_lshlrev_b64 v[44:45], 2, v[44:45]
	v_lshlrev_b64 v[46:47], 6, v[34:35]
	v_lshl_add_u64 v[62:63], s[50:51], 0, v[44:45]
	v_lshl_add_u64 v[46:47], s[8:9], 0, v[46:47]
	v_lshlrev_b32_e32 v0, 1, v36
	v_lshl_add_u64 v[60:61], s[48:49], 0, v[44:45]
	global_load_dwordx4 v[56:59], v[62:63], off
	v_lshl_add_u64 v[48:49], v[46:47], 0, v[0:1]
	global_load_dwordx4 v[44:47], v[60:61], off
	global_load_dwordx4 v[204:207], v[62:63], off offset:32
	global_load_dwordx4 v[208:211], v[60:61], off offset:32
	v_pk_mul_f32 v[18:19], v[18:19], v[40:41] op_sel_hi:[1,0]
	v_pk_mul_f32 v[26:27], v[26:27], v[40:41] op_sel_hi:[1,0]
	v_pk_mul_f32 v[20:21], v[20:21], v[40:41] op_sel_hi:[1,0]
	v_pk_mul_f32 v[22:23], v[22:23], v[40:41] op_sel_hi:[1,0]
	v_pk_mul_f32 v[30:31], v[30:31], v[40:41] op_sel_hi:[1,0]
	s_waitcnt vmcnt(3)
	v_pk_mul_f32 v[64:65], v[18:19], v[56:57]
	s_waitcnt vmcnt(2)
	v_pk_fma_f32 v[64:65], v[26:27], v[44:45], v[64:65]
	v_pk_mul_f32 v[26:27], v[26:27], v[56:57]
	v_mov_b32_e32 v56, 0
	v_pk_fma_f32 v[18:19], v[18:19], v[44:45], v[26:27] neg_lo:[0,0,1] neg_hi:[0,0,1]
	v_pk_mul_f32 v[26:27], v[28:29], v[40:41] op_sel_hi:[1,0]
	v_pk_mul_f32 v[28:29], v[20:21], v[58:59]
	v_cvt_pk_bf16_f32 v18, v18, v19
	v_pk_fma_f32 v[28:29], v[26:27], v[46:47], v[28:29]
	v_pk_mul_f32 v[26:27], v[26:27], v[58:59]
	s_nop 0
	v_pk_fma_f32 v[20:21], v[20:21], v[46:47], v[26:27] neg_lo:[0,0,1] neg_hi:[0,0,1]
	s_nop 0
	v_cvt_pk_bf16_f32 v19, v20, v21
	global_store_dwordx2 v[48:49], v[18:19], off
	v_cvt_pk_bf16_f32 v18, v64, v65
	v_cvt_pk_bf16_f32 v19, v28, v29
	global_store_dwordx2 v[48:49], v[18:19], off offset:32
	s_waitcnt vmcnt(3)
	v_pk_mul_f32 v[44:45], v[22:23], v[204:205]
	v_pk_mul_f32 v[26:27], v[30:31], v[204:205]
	s_waitcnt vmcnt(2)
	v_pk_fma_f32 v[44:45], v[30:31], v[208:209], v[44:45]
	v_pk_fma_f32 v[18:19], v[22:23], v[208:209], v[26:27] neg_lo:[0,0,1] neg_hi:[0,0,1]
	v_pk_mul_f32 v[22:23], v[24:25], v[40:41] op_sel_hi:[1,0]
	v_pk_mul_f32 v[24:25], v[32:33], v[40:41] op_sel_hi:[1,0]
	v_pk_mul_f32 v[26:27], v[22:23], v[206:207]
	v_cvt_pk_bf16_f32 v18, v18, v19
	v_pk_fma_f32 v[26:27], v[24:25], v[210:211], v[26:27]
	v_pk_mul_f32 v[24:25], v[24:25], v[206:207]
	s_nop 0
	v_pk_fma_f32 v[20:21], v[22:23], v[210:211], v[24:25] neg_lo:[0,0,1] neg_hi:[0,0,1]
	s_nop 0
	v_cvt_pk_bf16_f32 v19, v20, v21
	global_store_dwordx2 v[48:49], v[18:19], off offset:16
	v_cvt_pk_bf16_f32 v18, v44, v45
	v_cvt_pk_bf16_f32 v19, v26, v27
	v_mov_b32_e32 v44, v37
	global_store_dwordx2 v[48:49], v[18:19], off offset:48
